# down-projection full residual epilogue with a quarter tile of x loads in flight (on top of the previous combination)
# speedup vs baseline: 1.0293x; 1.0073x over previous
.LBB0_163:
	s_andn2_b64 vcc, exec, s[72:73]
	s_cbranch_vccnz .LBB0_165
	v_lshlrev_b64 v[156:157], 13, v[194:195]
	v_lshl_add_u64 v[156:157], s[60:61], 0, v[156:157]
	v_lshlrev_b64 v[194:195], 2, v[182:183]
	v_lshl_add_u64 v[182:183], v[156:157], 0, v[194:195]
	v_mov_b32_e32 v160, v182
	v_mov_b32_e32 v161, v183
	global_load_dwordx4 v[200:203], v[182:183], off
	global_load_dwordx4 v[204:207], v[182:183], off offset:16
	global_load_dwordx4 v[208:211], v[182:183], off offset:512
	global_load_dwordx4 v[212:215], v[182:183], off offset:528
	s_mov_b64 s[44:45], 0x20000
	v_lshl_add_u64 v[182:183], v[182:183], 0, s[44:45]
	global_load_dwordx4 v[216:219], v[182:183], off
	global_load_dwordx4 v[220:223], v[182:183], off offset:16
	global_load_dwordx4 v[224:227], v[182:183], off offset:512
	global_load_dwordx4 v[228:231], v[182:183], off offset:528
	s_mov_b64 s[44:45], 0x20000
	v_lshl_add_u64 v[182:183], v[182:183], 0, s[44:45]
	s_waitcnt vmcnt(0)
	v_pk_fma_f32 v[132:133], v[132:133], v[148:149], v[202:203]
	v_pk_fma_f32 v[130:131], v[130:131], v[146:147], v[200:201]
	v_pk_fma_f32 v[128:129], v[128:129], v[144:145], v[206:207]
	v_pk_fma_f32 v[126:127], v[126:127], v[142:143], v[204:205]
	v_pk_fma_f32 v[100:101], v[100:101], v[140:141], v[210:211]
	v_pk_fma_f32 v[98:99], v[98:99], v[138:139], v[208:209]
	v_pk_fma_f32 v[96:97], v[96:97], v[136:137], v[214:215]
	v_pk_fma_f32 v[94:95], v[94:95], v[134:135], v[212:213]
	global_store_dwordx4 v[160:161], v[130:133], off
	global_store_dwordx4 v[160:161], v[126:129], off offset:16
	global_store_dwordx4 v[160:161], v[98:101], off offset:512
	global_store_dwordx4 v[160:161], v[94:97], off offset:528
	s_mov_b64 s[44:45], 0x20000
	v_lshl_add_u64 v[160:161], v[160:161], 0, s[44:45]
	v_pk_fma_f32 v[124:125], v[124:125], v[148:149], v[218:219]
	v_pk_fma_f32 v[122:123], v[122:123], v[146:147], v[216:217]
	v_pk_fma_f32 v[120:121], v[120:121], v[144:145], v[222:223]
	v_pk_fma_f32 v[118:119], v[118:119], v[142:143], v[220:221]
	v_pk_fma_f32 v[92:93], v[92:93], v[140:141], v[226:227]
	v_pk_fma_f32 v[90:91], v[90:91], v[138:139], v[224:225]
	v_pk_fma_f32 v[88:89], v[88:89], v[136:137], v[230:231]
	v_pk_fma_f32 v[86:87], v[86:87], v[134:135], v[228:229]
	global_store_dwordx4 v[160:161], v[122:125], off
	global_store_dwordx4 v[160:161], v[118:121], off offset:16
	global_store_dwordx4 v[160:161], v[90:93], off offset:512
	global_store_dwordx4 v[160:161], v[86:89], off offset:528
	s_mov_b64 s[44:45], 0x20000
	v_lshl_add_u64 v[160:161], v[160:161], 0, s[44:45]
	global_load_dwordx4 v[200:203], v[182:183], off
	global_load_dwordx4 v[204:207], v[182:183], off offset:16
	global_load_dwordx4 v[208:211], v[182:183], off offset:512
	global_load_dwordx4 v[212:215], v[182:183], off offset:528
	s_mov_b64 s[44:45], 0x20000
	v_lshl_add_u64 v[182:183], v[182:183], 0, s[44:45]
	global_load_dwordx4 v[216:219], v[182:183], off
	global_load_dwordx4 v[220:223], v[182:183], off offset:16
	global_load_dwordx4 v[224:227], v[182:183], off offset:512
	global_load_dwordx4 v[228:231], v[182:183], off offset:528
	s_mov_b64 s[44:45], 0xa0000
	v_lshl_add_u64 v[182:183], v[182:183], 0, s[44:45]
	global_load_dwordx4 v[130:133], v[182:183], off
	global_load_dwordx4 v[126:129], v[182:183], off offset:16
	global_load_dwordx4 v[98:101], v[182:183], off offset:512
	global_load_dwordx4 v[94:97], v[182:183], off offset:528
	s_mov_b64 s[44:45], 0x20000
	v_lshl_add_u64 v[182:183], v[182:183], 0, s[44:45]
	global_load_dwordx4 v[122:125], v[182:183], off
	global_load_dwordx4 v[118:121], v[182:183], off offset:16
	global_load_dwordx4 v[90:93], v[182:183], off offset:512
	global_load_dwordx4 v[86:89], v[182:183], off offset:528
	s_mov_b64 s[44:45], 0x20000
	v_lshl_add_u64 v[182:183], v[182:183], 0, s[44:45]
	s_waitcnt vmcnt(8)
	v_pk_fma_f32 v[116:117], v[116:117], v[148:149], v[202:203]
	v_pk_fma_f32 v[114:115], v[114:115], v[146:147], v[200:201]
	v_pk_fma_f32 v[112:113], v[112:113], v[144:145], v[206:207]
	v_pk_fma_f32 v[110:111], v[110:111], v[142:143], v[204:205]
	v_pk_fma_f32 v[84:85], v[84:85], v[140:141], v[210:211]
	v_pk_fma_f32 v[82:83], v[82:83], v[138:139], v[208:209]
	v_pk_fma_f32 v[80:81], v[80:81], v[136:137], v[214:215]
	v_pk_fma_f32 v[78:79], v[78:79], v[134:135], v[212:213]
	global_store_dwordx4 v[160:161], v[114:117], off
	global_store_dwordx4 v[160:161], v[110:113], off offset:16
	global_store_dwordx4 v[160:161], v[82:85], off offset:512
	global_store_dwordx4 v[160:161], v[78:81], off offset:528
	s_mov_b64 s[44:45], 0x20000
	v_lshl_add_u64 v[160:161], v[160:161], 0, s[44:45]
	v_pk_fma_f32 v[108:109], v[108:109], v[148:149], v[218:219]
	v_pk_fma_f32 v[106:107], v[106:107], v[146:147], v[216:217]
	v_pk_fma_f32 v[104:105], v[104:105], v[144:145], v[222:223]
	v_pk_fma_f32 v[102:103], v[102:103], v[142:143], v[220:221]
	v_pk_fma_f32 v[76:77], v[76:77], v[140:141], v[226:227]
	v_pk_fma_f32 v[74:75], v[74:75], v[138:139], v[224:225]
	v_pk_fma_f32 v[72:73], v[72:73], v[136:137], v[230:231]
	v_pk_fma_f32 v[70:71], v[70:71], v[134:135], v[228:229]
	global_store_dwordx4 v[160:161], v[106:109], off
	global_store_dwordx4 v[160:161], v[102:105], off offset:16
	global_store_dwordx4 v[160:161], v[74:77], off offset:512
	global_store_dwordx4 v[160:161], v[70:73], off offset:528
	s_mov_b64 s[44:45], 0xa0000
	v_lshl_add_u64 v[160:161], v[160:161], 0, s[44:45]
	global_load_dwordx4 v[200:203], v[182:183], off
	global_load_dwordx4 v[204:207], v[182:183], off offset:16
	global_load_dwordx4 v[208:211], v[182:183], off offset:512
	global_load_dwordx4 v[212:215], v[182:183], off offset:528
	s_mov_b64 s[44:45], 0x20000
	v_lshl_add_u64 v[182:183], v[182:183], 0, s[44:45]
	global_load_dwordx4 v[216:219], v[182:183], off
	global_load_dwordx4 v[220:223], v[182:183], off offset:16
	global_load_dwordx4 v[224:227], v[182:183], off offset:512
	global_load_dwordx4 v[228:231], v[182:183], off offset:528
	s_waitcnt vmcnt(8)
	v_pk_fma_f32 v[68:69], v[68:69], v[148:149], v[132:133]
	v_pk_fma_f32 v[66:67], v[66:67], v[146:147], v[130:131]
	v_pk_fma_f32 v[64:65], v[64:65], v[144:145], v[128:129]
	v_pk_fma_f32 v[62:63], v[62:63], v[142:143], v[126:127]
	v_pk_fma_f32 v[36:37], v[36:37], v[140:141], v[100:101]
	v_pk_fma_f32 v[34:35], v[34:35], v[138:139], v[98:99]
	v_pk_fma_f32 v[32:33], v[32:33], v[136:137], v[96:97]
	v_pk_fma_f32 v[30:31], v[30:31], v[134:135], v[94:95]
	global_store_dwordx4 v[160:161], v[66:69], off
	global_store_dwordx4 v[160:161], v[62:65], off offset:16
	global_store_dwordx4 v[160:161], v[34:37], off offset:512
	global_store_dwordx4 v[160:161], v[30:33], off offset:528
	s_mov_b64 s[44:45], 0x20000
	v_lshl_add_u64 v[160:161], v[160:161], 0, s[44:45]
	v_pk_fma_f32 v[60:61], v[60:61], v[148:149], v[124:125]
	v_pk_fma_f32 v[58:59], v[58:59], v[146:147], v[122:123]
	v_pk_fma_f32 v[56:57], v[56:57], v[144:145], v[120:121]
	v_pk_fma_f32 v[54:55], v[54:55], v[142:143], v[118:119]
	v_pk_fma_f32 v[28:29], v[28:29], v[140:141], v[92:93]
	v_pk_fma_f32 v[26:27], v[26:27], v[138:139], v[90:91]
	v_pk_fma_f32 v[24:25], v[24:25], v[136:137], v[88:89]
	v_pk_fma_f32 v[22:23], v[22:23], v[134:135], v[86:87]
	global_store_dwordx4 v[160:161], v[58:61], off
	global_store_dwordx4 v[160:161], v[54:57], off offset:16
	global_store_dwordx4 v[160:161], v[26:29], off offset:512
	global_store_dwordx4 v[160:161], v[22:25], off offset:528
	s_mov_b64 s[44:45], 0x20000
	v_lshl_add_u64 v[160:161], v[160:161], 0, s[44:45]
	s_waitcnt vmcnt(0)
	v_pk_fma_f32 v[52:53], v[52:53], v[148:149], v[202:203]
	v_pk_fma_f32 v[50:51], v[50:51], v[146:147], v[200:201]
	v_pk_fma_f32 v[48:49], v[48:49], v[144:145], v[206:207]
	v_pk_fma_f32 v[46:47], v[46:47], v[142:143], v[204:205]
	v_pk_fma_f32 v[20:21], v[20:21], v[140:141], v[210:211]
	v_pk_fma_f32 v[18:19], v[18:19], v[138:139], v[208:209]
	v_pk_fma_f32 v[12:13], v[12:13], v[136:137], v[214:215]
	v_pk_fma_f32 v[10:11], v[10:11], v[134:135], v[212:213]
	global_store_dwordx4 v[160:161], v[50:53], off
	global_store_dwordx4 v[160:161], v[46:49], off offset:16
	global_store_dwordx4 v[160:161], v[18:21], off offset:512
	global_store_dwordx4 v[160:161], v[10:13], off offset:528
	s_mov_b64 s[44:45], 0x20000
	v_lshl_add_u64 v[160:161], v[160:161], 0, s[44:45]
	v_pk_fma_f32 v[44:45], v[44:45], v[148:149], v[218:219]
	v_pk_fma_f32 v[42:43], v[42:43], v[146:147], v[216:217]
	v_pk_fma_f32 v[40:41], v[40:41], v[144:145], v[222:223]
	v_pk_fma_f32 v[38:39], v[38:39], v[142:143], v[220:221]
	v_pk_fma_f32 v[8:9], v[8:9], v[140:141], v[226:227]
	v_pk_fma_f32 v[6:7], v[6:7], v[138:139], v[224:225]
	v_pk_fma_f32 v[2:3], v[2:3], v[136:137], v[230:231]
	v_pk_fma_f32 v[0:1], v[0:1], v[134:135], v[228:229]
	global_store_dwordx4 v[160:161], v[42:45], off
	global_store_dwordx4 v[160:161], v[38:41], off offset:16
	global_store_dwordx4 v[160:161], v[6:9], off offset:512
	global_store_dwordx4 v[160:161], v[0:3], off offset:528
